# attention key loop: per-segment s_setprio for waves 4-7 (priority 0 during the first QK block of an iteration, 1 during PV1/QK2/PV2) so both waves of a SIMD reach the per-iteration barrier together
# speedup vs baseline: 1.0111x; 1.0039x over previous
.LBB0_729:
.LBB0_730:
	v_readfirstlane_b32 vcc_lo, v199
	s_bitcmp1_b32 vcc_lo, 8
	s_cbranch_scc0 .Lpsq_1
	s_setprio 0

.LBB0_732:
	v_readfirstlane_b32 vcc_lo, v199
	s_bitcmp1_b32 vcc_lo, 8
	s_cbranch_scc0 .Lpsq_2
	s_setprio 1
